# MLA sample unit: QK K-fragment reads prefetched through a 9-slot register ring, lazy rescale threshold, cross-half max deferred
# speedup vs baseline: 1.0484x; 1.0013x over previous
.LBB0_1029:
	ds_read_b128 v[64:67], v215
	ds_read_b128 v[218:221], v215 offset:32
	ds_read_b128 v[222:225], v215 offset:64
	ds_read_b128 v[226:229], v215 offset:96
	ds_read_b128 v[230:233], v215 offset:128
	ds_read_b128 v[234:237], v215 offset:160
	ds_read_b128 v[238:241], v215 offset:192
	ds_read_b128 v[242:245], v215 offset:224
	ds_read_b128 v[246:249], v215 offset:256
	ds_read_b128 v[250:253], v215 offset:288
	s_cmpk_lg_i32 s47, 0x1000
	s_cselect_b64 vcc, -1, 0
	s_waitcnt lgkmcnt(9)
	v_mfma_f32_32x32x16_bf16 v[64:79], v[64:67], v[80:83], 0
	s_waitcnt lgkmcnt(8)
	v_mfma_f32_32x32x16_bf16 v[64:79], v[218:221], v[84:87], v[64:79]
	ds_read_b128 v[218:221], v215 offset:320
	s_waitcnt lgkmcnt(8)
	v_mfma_f32_32x32x16_bf16 v[64:79], v[222:225], v[88:91], v[64:79]
	ds_read_b128 v[222:225], v215 offset:352
	s_waitcnt lgkmcnt(8)
	v_mfma_f32_32x32x16_bf16 v[64:79], v[226:229], v[92:95], v[64:79]
	ds_read_b128 v[226:229], v215 offset:384
	s_waitcnt lgkmcnt(8)
	v_mfma_f32_32x32x16_bf16 v[64:79], v[230:233], v[96:99], v[64:79]
	ds_read_b128 v[230:233], v215 offset:416
	s_waitcnt lgkmcnt(8)
	v_mfma_f32_32x32x16_bf16 v[64:79], v[234:237], v[100:103], v[64:79]
	ds_read_b128 v[234:237], v215 offset:448
	s_waitcnt lgkmcnt(8)
	v_mfma_f32_32x32x16_bf16 v[64:79], v[238:241], v[104:107], v[64:79]
	ds_read_b128 v[238:241], v215 offset:480
	s_waitcnt lgkmcnt(8)
	v_mfma_f32_32x32x16_bf16 v[64:79], v[242:245], v[108:111], v[64:79]
	ds_read_b128 v[242:245], v215 offset:512
	s_waitcnt lgkmcnt(8)
	v_mfma_f32_32x32x16_bf16 v[64:79], v[246:249], v[112:115], v[64:79]
	ds_read_b128 v[246:249], v215 offset:544
	s_waitcnt lgkmcnt(8)
	v_mfma_f32_32x32x16_bf16 v[64:79], v[250:253], v[116:119], v[64:79]
	s_waitcnt lgkmcnt(7)
	v_mfma_f32_32x32x16_bf16 v[64:79], v[218:221], v[120:123], v[64:79]
	s_waitcnt lgkmcnt(6)
	v_mfma_f32_32x32x16_bf16 v[64:79], v[222:225], v[124:127], v[64:79]
	s_waitcnt lgkmcnt(5)
	v_mfma_f32_32x32x16_bf16 v[64:79], v[226:229], v[128:131], v[64:79]
	s_waitcnt lgkmcnt(4)
	v_mfma_f32_32x32x16_bf16 v[64:79], v[230:233], v[132:135], v[64:79]
	s_waitcnt lgkmcnt(3)
	v_mfma_f32_32x32x16_bf16 v[64:79], v[234:237], v[136:139], v[64:79]
	s_waitcnt lgkmcnt(2)
	v_mfma_f32_32x32x16_bf16 v[64:79], v[238:241], v[140:143], v[64:79]
	s_waitcnt lgkmcnt(1)
	v_mfma_f32_32x32x16_bf16 v[64:79], v[242:245], v[144:147], v[64:79]
	s_waitcnt lgkmcnt(0)
	v_mfma_f32_32x32x16_bf16 v[64:79], v[246:249], v[148:151], v[64:79]
	s_nop 11
	v_max_f32_e32 v218, v65, v65
	v_max_f32_e32 v219, v64, v64
	v_max_f32_e32 v218, v219, v218
	v_max3_f32 v218, v218, v66, v67
	v_max3_f32 v218, v218, v68, v69
	v_cndmask_b32_e32 v72, v202, v72, vcc
	v_cndmask_b32_e32 v73, v202, v73, vcc
	v_max3_f32 v218, v218, v70, v71
	v_cndmask_b32_e32 v74, v202, v74, vcc
	v_cndmask_b32_e32 v75, v202, v75, vcc
	v_max3_f32 v218, v218, v72, v73
	v_cndmask_b32_e32 v76, v202, v76, vcc
	v_cndmask_b32_e32 v77, v202, v77, vcc
	v_max3_f32 v218, v218, v74, v75
	v_cndmask_b32_e32 v78, v202, v78, vcc
	v_cndmask_b32_e32 v79, v202, v79, vcc
	v_max3_f32 v218, v218, v76, v77
	v_max3_f32 v218, v218, v78, v79
	v_sub_f32_e32 v219, v218, v217
	v_cmp_lt_f32_e32 vcc, 0x41000000, v219
	s_cbranch_vccz .LBB0_1031
	v_mov_b32_e32 v219, v218
	s_nop 1
	v_permlane32_swap_b32_e32 v218, v219
	v_max_f32_e32 v218, v218, v219
	v_max_f32_e32 v219, v217, v218
	v_sub_f32_e32 v217, v217, v219
	v_exp_f32_e32 v218, v217
	v_mov_b32_e32 v217, v219
	v_pk_mul_f32 v[62:63], v[62:63], v[218:219] op_sel_hi:[1,0]
	v_pk_mul_f32 v[60:61], v[60:61], v[218:219] op_sel_hi:[1,0]
	v_pk_mul_f32 v[58:59], v[58:59], v[218:219] op_sel_hi:[1,0]
	v_pk_mul_f32 v[56:57], v[56:57], v[218:219] op_sel_hi:[1,0]
	v_pk_mul_f32 v[54:55], v[54:55], v[218:219] op_sel_hi:[1,0]
	v_pk_mul_f32 v[52:53], v[52:53], v[218:219] op_sel_hi:[1,0]
	v_pk_mul_f32 v[50:51], v[50:51], v[218:219] op_sel_hi:[1,0]
	v_pk_mul_f32 v[48:49], v[48:49], v[218:219] op_sel_hi:[1,0]
	v_pk_mul_f32 v[46:47], v[46:47], v[218:219] op_sel_hi:[1,0]
	v_pk_mul_f32 v[44:45], v[44:45], v[218:219] op_sel_hi:[1,0]
	v_pk_mul_f32 v[42:43], v[42:43], v[218:219] op_sel_hi:[1,0]
	v_pk_mul_f32 v[40:41], v[40:41], v[218:219] op_sel_hi:[1,0]
	v_pk_mul_f32 v[38:39], v[38:39], v[218:219] op_sel_hi:[1,0]
	v_pk_mul_f32 v[36:37], v[36:37], v[218:219] op_sel_hi:[1,0]
	v_pk_mul_f32 v[34:35], v[34:35], v[218:219] op_sel_hi:[1,0]
	v_pk_mul_f32 v[32:33], v[32:33], v[218:219] op_sel_hi:[1,0]
	v_pk_mul_f32 v[30:31], v[30:31], v[218:219] op_sel_hi:[1,0]
	v_pk_mul_f32 v[28:29], v[28:29], v[218:219] op_sel_hi:[1,0]
	v_pk_mul_f32 v[26:27], v[26:27], v[218:219] op_sel_hi:[1,0]
	v_pk_mul_f32 v[24:25], v[24:25], v[218:219] op_sel_hi:[1,0]
	v_pk_mul_f32 v[22:23], v[22:23], v[218:219] op_sel_hi:[1,0]
	v_pk_mul_f32 v[20:21], v[20:21], v[218:219] op_sel_hi:[1,0]
	v_pk_mul_f32 v[18:19], v[18:19], v[218:219] op_sel_hi:[1,0]
	v_pk_mul_f32 v[16:17], v[16:17], v[218:219] op_sel_hi:[1,0]
	v_pk_mul_f32 v[14:15], v[14:15], v[218:219] op_sel_hi:[1,0]
	v_pk_mul_f32 v[12:13], v[12:13], v[218:219] op_sel_hi:[1,0]
	v_pk_mul_f32 v[10:11], v[10:11], v[218:219] op_sel_hi:[1,0]
	v_pk_mul_f32 v[8:9], v[8:9], v[218:219] op_sel_hi:[1,0]
	v_pk_mul_f32 v[6:7], v[6:7], v[218:219] op_sel_hi:[1,0]
	v_pk_mul_f32 v[4:5], v[4:5], v[218:219] op_sel_hi:[1,0]
	v_pk_mul_f32 v[2:3], v[2:3], v[218:219] op_sel_hi:[1,0]
	v_pk_mul_f32 v[0:1], v[0:1], v[218:219] op_sel_hi:[1,0]
	v_mul_f32_e32 v214, v214, v218

.LBB0_1039:
	v_add_f32_e32 v64, 0, v64
	v_add_f32_e32 v64, v65, v64
	v_add_f32_e32 v64, v66, v64
	v_add_f32_e32 v64, v67, v64
	v_add_f32_e32 v64, v68, v64
	v_add_f32_e32 v64, v69, v64
	v_add_f32_e32 v64, v70, v64
	v_add_f32_e32 v64, v71, v64
	v_add_f32_e32 v64, v72, v64
	v_add_f32_e32 v64, v73, v64
	v_add_f32_e32 v64, v74, v64
	v_add_f32_e32 v64, v75, v64
	v_add_f32_e32 v64, v76, v64
	v_add_f32_e32 v64, v77, v64
	v_add_f32_e32 v64, v78, v64
	v_add_f32_e32 v64, v79, v64
	v_add_f32_e32 v214, v214, v64
	s_andn2_b64 vcc, exec, s[10:11]
	s_waitcnt lgkmcnt(0)
	s_barrier
	s_cbranch_vccnz .LBB0_1049
	ds_read_b128 v[64:67], v215 offset:18944
	ds_read_b128 v[218:221], v215 offset:18976
	ds_read_b128 v[222:225], v215 offset:19008
	ds_read_b128 v[226:229], v215 offset:19040
	ds_read_b128 v[230:233], v215 offset:19072
	ds_read_b128 v[234:237], v215 offset:19104
	ds_read_b128 v[238:241], v215 offset:19136
	ds_read_b128 v[242:245], v215 offset:19168
	ds_read_b128 v[246:249], v215 offset:19200
	ds_read_b128 v[250:253], v215 offset:19232
	s_waitcnt lgkmcnt(9)
	v_mfma_f32_32x32x16_bf16 v[64:79], v[64:67], v[80:83], 0
	s_waitcnt lgkmcnt(8)
	v_mfma_f32_32x32x16_bf16 v[64:79], v[218:221], v[84:87], v[64:79]
	ds_read_b128 v[218:221], v215 offset:19264
	s_waitcnt lgkmcnt(8)
	v_mfma_f32_32x32x16_bf16 v[64:79], v[222:225], v[88:91], v[64:79]
	ds_read_b128 v[222:225], v215 offset:19296
	s_waitcnt lgkmcnt(8)
	v_mfma_f32_32x32x16_bf16 v[64:79], v[226:229], v[92:95], v[64:79]
	ds_read_b128 v[226:229], v215 offset:19328
	s_waitcnt lgkmcnt(8)
	v_mfma_f32_32x32x16_bf16 v[64:79], v[230:233], v[96:99], v[64:79]
	ds_read_b128 v[230:233], v215 offset:19360
	s_waitcnt lgkmcnt(8)
	v_mfma_f32_32x32x16_bf16 v[64:79], v[234:237], v[100:103], v[64:79]
	ds_read_b128 v[234:237], v215 offset:19392
	s_waitcnt lgkmcnt(8)
	v_mfma_f32_32x32x16_bf16 v[64:79], v[238:241], v[104:107], v[64:79]
	ds_read_b128 v[238:241], v215 offset:19424
	s_waitcnt lgkmcnt(8)
	v_mfma_f32_32x32x16_bf16 v[64:79], v[242:245], v[108:111], v[64:79]
	ds_read_b128 v[242:245], v215 offset:19456
	s_waitcnt lgkmcnt(8)
	v_mfma_f32_32x32x16_bf16 v[64:79], v[246:249], v[112:115], v[64:79]
	ds_read_b128 v[246:249], v215 offset:19488
	s_waitcnt lgkmcnt(8)
	v_mfma_f32_32x32x16_bf16 v[64:79], v[250:253], v[116:119], v[64:79]
	s_waitcnt lgkmcnt(7)
	v_mfma_f32_32x32x16_bf16 v[64:79], v[218:221], v[120:123], v[64:79]
	s_waitcnt lgkmcnt(6)
	v_mfma_f32_32x32x16_bf16 v[64:79], v[222:225], v[124:127], v[64:79]
	s_waitcnt lgkmcnt(5)
	v_mfma_f32_32x32x16_bf16 v[64:79], v[226:229], v[128:131], v[64:79]
	s_waitcnt lgkmcnt(4)
	v_mfma_f32_32x32x16_bf16 v[64:79], v[230:233], v[132:135], v[64:79]
	s_waitcnt lgkmcnt(3)
	v_mfma_f32_32x32x16_bf16 v[64:79], v[234:237], v[136:139], v[64:79]
	s_waitcnt lgkmcnt(2)
	v_mfma_f32_32x32x16_bf16 v[64:79], v[238:241], v[140:143], v[64:79]
	s_waitcnt lgkmcnt(1)
	v_mfma_f32_32x32x16_bf16 v[64:79], v[242:245], v[144:147], v[64:79]
	s_waitcnt lgkmcnt(0)
	v_mfma_f32_32x32x16_bf16 v[64:79], v[246:249], v[148:151], v[64:79]
	s_nop 11
	v_max_f32_e32 v218, v65, v65
	v_max_f32_e32 v219, v64, v64
	v_max_f32_e32 v218, v219, v218
	v_max3_f32 v218, v218, v66, v67
	v_max3_f32 v218, v218, v68, v69
	v_max3_f32 v218, v218, v70, v71
	v_max3_f32 v218, v218, v72, v73
	v_max3_f32 v218, v218, v74, v75
	v_max3_f32 v218, v218, v76, v77
	v_max3_f32 v218, v218, v78, v79
	v_sub_f32_e32 v219, v218, v217
	v_cmp_lt_f32_e32 vcc, 0x41000000, v219
	s_cbranch_vccz .LBB0_1042
	v_mov_b32_e32 v219, v218
	s_nop 1
	v_permlane32_swap_b32_e32 v218, v219
	v_max_f32_e32 v218, v218, v219
	v_max_f32_e32 v219, v217, v218
	v_sub_f32_e32 v217, v217, v219
	v_exp_f32_e32 v218, v217
	v_mov_b32_e32 v217, v219
	v_pk_mul_f32 v[62:63], v[62:63], v[218:219] op_sel_hi:[1,0]
	v_pk_mul_f32 v[60:61], v[60:61], v[218:219] op_sel_hi:[1,0]
	v_pk_mul_f32 v[58:59], v[58:59], v[218:219] op_sel_hi:[1,0]
	v_pk_mul_f32 v[56:57], v[56:57], v[218:219] op_sel_hi:[1,0]
	v_pk_mul_f32 v[54:55], v[54:55], v[218:219] op_sel_hi:[1,0]
	v_pk_mul_f32 v[52:53], v[52:53], v[218:219] op_sel_hi:[1,0]
	v_pk_mul_f32 v[50:51], v[50:51], v[218:219] op_sel_hi:[1,0]
	v_pk_mul_f32 v[48:49], v[48:49], v[218:219] op_sel_hi:[1,0]
	v_pk_mul_f32 v[46:47], v[46:47], v[218:219] op_sel_hi:[1,0]
	v_pk_mul_f32 v[44:45], v[44:45], v[218:219] op_sel_hi:[1,0]
	v_pk_mul_f32 v[42:43], v[42:43], v[218:219] op_sel_hi:[1,0]
	v_pk_mul_f32 v[40:41], v[40:41], v[218:219] op_sel_hi:[1,0]
	v_pk_mul_f32 v[38:39], v[38:39], v[218:219] op_sel_hi:[1,0]
	v_pk_mul_f32 v[36:37], v[36:37], v[218:219] op_sel_hi:[1,0]
	v_pk_mul_f32 v[34:35], v[34:35], v[218:219] op_sel_hi:[1,0]
	v_pk_mul_f32 v[32:33], v[32:33], v[218:219] op_sel_hi:[1,0]
	v_pk_mul_f32 v[30:31], v[30:31], v[218:219] op_sel_hi:[1,0]
	v_pk_mul_f32 v[28:29], v[28:29], v[218:219] op_sel_hi:[1,0]
	v_pk_mul_f32 v[26:27], v[26:27], v[218:219] op_sel_hi:[1,0]
	v_pk_mul_f32 v[24:25], v[24:25], v[218:219] op_sel_hi:[1,0]
	v_pk_mul_f32 v[22:23], v[22:23], v[218:219] op_sel_hi:[1,0]
	v_pk_mul_f32 v[20:21], v[20:21], v[218:219] op_sel_hi:[1,0]
	v_pk_mul_f32 v[18:19], v[18:19], v[218:219] op_sel_hi:[1,0]
	v_pk_mul_f32 v[16:17], v[16:17], v[218:219] op_sel_hi:[1,0]
	v_pk_mul_f32 v[14:15], v[14:15], v[218:219] op_sel_hi:[1,0]
	v_pk_mul_f32 v[12:13], v[12:13], v[218:219] op_sel_hi:[1,0]
	v_pk_mul_f32 v[10:11], v[10:11], v[218:219] op_sel_hi:[1,0]
	v_pk_mul_f32 v[8:9], v[8:9], v[218:219] op_sel_hi:[1,0]
	v_pk_mul_f32 v[6:7], v[6:7], v[218:219] op_sel_hi:[1,0]
	v_pk_mul_f32 v[4:5], v[4:5], v[218:219] op_sel_hi:[1,0]
	v_pk_mul_f32 v[2:3], v[2:3], v[218:219] op_sel_hi:[1,0]
	v_pk_mul_f32 v[0:1], v[0:1], v[218:219] op_sel_hi:[1,0]
	v_mul_f32_e32 v214, v214, v218
